# attention XCD remap + SGU item loads up front (v2) + attention z loads up front
# baseline (speedup 1.0000x reference)
; __device__ __forceinline__ void sgu_phase(LAS unsigned char* lds, const bf16_t* U, const bf16_t* GV, const bf16_t* SZ, const float* stats, const float* vg, const float* vb,
;                                           const bf16_t* wsb, const float* b_s, bf16_t* Y, int G, int bid) {
;     ...
;     for (int itl = bid; itl < 1024; itl += G) {
;         const int it = xmap ? ((bid & 7) * 128 + (bid >> 3) + 32 * (itl >> 8)) : itl;
;         const int ci = it >> 4, g = it & 15, row0 = ci * 128;
;         __syncthreads();
;         if (tid < 128) {
;             const float* sp = stats + (size_t)(row0 + tid) * 64; float s = 0.f, ss = 0.f;
; #pragma unroll
;             for (int i = 0; i < 16; ++i) { const f32x4 q = *(const f32x4*)(sp + i * 4); s += q[0] + q[2]; ss += q[1] + q[3]; }
;             const float mean = s * (1.0f / DM), var = ss * (1.0f / DM) - mean * mean;
;             rstat[tid] = (f32x2){mean, rsqrtf(var + 1e-5f)};
;         }
;         __syncthreads();
; #pragma unroll
;         for (int i = 0; i < 4; ++i) {
;             const int id = tid + 512 * i, r = id >> 4, cc = id & 15;
;             const u32x4 w = *(const u32x4*)(GV + (size_t)(row0 + r) * DM + g * 128 + cc * 8);
;             const f32x2 st = rstat[r];
;             const f32x4 g0 = *(const f32x4*)(vg + g * 128 + cc * 8), g1 = *(const f32x4*)(vg + g * 128 + cc * 8 + 4);
;             const f32x4 b0 = *(const f32x4*)(vb + g * 128 + cc * 8), b1 = *(const f32x4*)(vb + g * 128 + cc * 8 + 4);
.LBB0_235:
	s_ashr_i32 s0, s26, 3
	s_andn2_b32 s0, s0, 31
	s_add_i32 s18, s3, s0
	s_and_b64 s[0:1], s[6:7], exec
	s_cselect_b32 s18, s18, s26
	s_lshl_b32 s0, s18, 3
	s_and_b32 s27, s0, 0xffffff80
	s_waitcnt lgkmcnt(0)
	s_barrier
	s_lshl_b32 s24, s18, 7
	s_and_b32 s36, s24, 0x780
	s_mov_b32 s25, 0
	v_add_u32_e32 v240, s27, v47
	v_ashrrev_i32_e32 v241, 31, v240
	v_lshlrev_b64 v[240:241], 11, v[240:241]
	v_or3_b32 v240, v240, v40, s36
	v_lshlrev_b64 v[240:241], 1, v[240:241]
	v_lshl_add_u64 v[240:241], s[8:9], 0, v[240:241]
	v_add_lshl_u32 v242, s36, v47, 2
	global_load_dword v126, v242, s[28:29]
	global_load_dwordx2 v[110:111], v[240:241], off
	global_load_dwordx2 v[112:113], v[240:241], off offset:32
	global_load_dwordx2 v[114:115], v[240:241], off offset:64
	global_load_dwordx2 v[116:117], v[240:241], off offset:96
	global_load_dwordx2 v[118:119], v[240:241], off offset:128
	global_load_dwordx2 v[120:121], v[240:241], off offset:160
	global_load_dwordx2 v[122:123], v[240:241], off offset:192
	global_load_dwordx2 v[124:125], v[240:241], off offset:224
	s_lshl_b32 s24, s36, 1
	v_lshl_add_u64 v[236:237], v[34:35], 0, s[24:25]
	s_lshl_b32 s24, s36, 2
	v_lshl_add_u64 v[244:245], v[38:39], 0, s[24:25]
	v_lshl_add_u64 v[246:247], v[36:37], 0, s[24:25]
	v_or_b32_e32 v238, s27, v214
	v_ashrrev_i32_e32 v239, 31, v238
	v_lshlrev_b64 v[238:239], 12, v[238:239]
	v_lshl_add_u64 v[238:239], v[236:237], 0, v[238:239]
	global_load_dwordx4 v[130:133], v[238:239], off
	global_load_dwordx4 v[134:137], v[244:245], off
	global_load_dwordx4 v[138:141], v[246:247], off
	global_load_dwordx4 v[142:145], v[246:247], off offset:16
	global_load_dwordx4 v[146:149], v[244:245], off offset:16
	v_or_b32_e32 v238, s27, v50
	v_ashrrev_i32_e32 v239, 31, v238
	v_lshlrev_b64 v[238:239], 12, v[238:239]
	v_lshl_add_u64 v[238:239], v[236:237], 0, v[238:239]
	global_load_dwordx4 v[170:173], v[238:239], off
	global_load_dwordx4 v[174:177], v[244:245], off
	global_load_dwordx4 v[178:181], v[246:247], off
	global_load_dwordx4 v[182:185], v[246:247], off offset:16
	global_load_dwordx4 v[186:189], v[244:245], off offset:16
	v_or_b32_e32 v238, s27, v52
	v_ashrrev_i32_e32 v239, 31, v238
	v_lshlrev_b64 v[238:239], 12, v[238:239]
	v_lshl_add_u64 v[238:239], v[236:237], 0, v[238:239]
	global_load_dwordx4 v[190:193], v[238:239], off
	global_load_dwordx4 v[194:197], v[244:245], off
	global_load_dwordx4 v[198:201], v[246:247], off
	global_load_dwordx4 v[202:205], v[246:247], off offset:16
	global_load_dwordx4 v[206:209], v[244:245], off offset:16
	v_add_u32_e32 v238, s27, v54
	v_ashrrev_i32_e32 v239, 31, v238
	v_lshlrev_b64 v[238:239], 12, v[238:239]
	v_lshl_add_u64 v[238:239], v[236:237], 0, v[238:239]
	global_load_dwordx4 v[216:219], v[238:239], off
	global_load_dwordx4 v[220:223], v[244:245], off
	global_load_dwordx4 v[224:227], v[246:247], off
	global_load_dwordx4 v[228:231], v[246:247], off offset:16
	global_load_dwordx4 v[232:235], v[244:245], off offset:16
	s_and_saveexec_b64 s[24:25], vcc
	s_cbranch_execz .LBB0_237
	v_or_b32_e32 v0, s27, v164
	v_ashrrev_i32_e32 v1, 31, v0
	v_lshlrev_b64 v[0:1], 8, v[0:1]
	v_lshl_add_u64 v[44:45], s[16:17], 0, v[0:1]
	global_load_dwordx4 v[0:3], v[44:45], off
	global_load_dwordx4 v[4:7], v[44:45], off offset:16
	global_load_dwordx4 v[8:11], v[44:45], off offset:32
	global_load_dwordx4 v[12:15], v[44:45], off offset:48
	global_load_dwordx4 v[16:19], v[44:45], off offset:64
	global_load_dwordx4 v[20:23], v[44:45], off offset:80
	global_load_dwordx4 v[24:27], v[44:45], off offset:96
	global_load_dwordx4 v[28:31], v[44:45], off offset:112
	global_load_dwordx4 v[70:73], v[44:45], off offset:128
	global_load_dwordx4 v[74:77], v[44:45], off offset:144
	global_load_dwordx4 v[78:81], v[44:45], off offset:160
	global_load_dwordx4 v[82:85], v[44:45], off offset:176
	global_load_dwordx4 v[86:89], v[44:45], off offset:192
	global_load_dwordx4 v[90:93], v[44:45], off offset:208
	global_load_dwordx4 v[94:97], v[44:45], off offset:224
	global_load_dwordx4 v[98:101], v[44:45], off offset:240
	s_waitcnt vmcnt(15)
	v_pk_add_f32 v[0:1], v[0:1], v[2:3]
	s_waitcnt vmcnt(14)
	v_pk_add_f32 v[2:3], v[4:5], v[6:7]
	v_pk_add_f32 v[0:1], v[0:1], 0 op_sel_hi:[1,0]
	s_waitcnt vmcnt(13)
	v_pk_add_f32 v[4:5], v[8:9], v[10:11]
	v_pk_add_f32 v[0:1], v[0:1], v[2:3]
	s_waitcnt vmcnt(12)
	v_pk_add_f32 v[6:7], v[12:13], v[14:15]
	v_pk_add_f32 v[0:1], v[0:1], v[4:5]
	s_waitcnt vmcnt(11)
	v_pk_add_f32 v[8:9], v[16:17], v[18:19]
	v_pk_add_f32 v[0:1], v[0:1], v[6:7]
	s_waitcnt vmcnt(10)
	v_pk_add_f32 v[10:11], v[20:21], v[22:23]
	v_pk_add_f32 v[0:1], v[0:1], v[8:9]
	s_waitcnt vmcnt(9)
	v_pk_add_f32 v[12:13], v[24:25], v[26:27]
	v_pk_add_f32 v[0:1], v[0:1], v[10:11]
	s_waitcnt vmcnt(8)
	v_pk_add_f32 v[14:15], v[28:29], v[30:31]
	v_pk_add_f32 v[0:1], v[0:1], v[12:13]
	s_waitcnt vmcnt(7)
	v_pk_add_f32 v[16:17], v[70:71], v[72:73]
	v_pk_add_f32 v[0:1], v[0:1], v[14:15]
	s_waitcnt vmcnt(6)
	v_pk_add_f32 v[18:19], v[74:75], v[76:77]
	v_pk_add_f32 v[0:1], v[0:1], v[16:17]
	s_waitcnt vmcnt(5)
	v_pk_add_f32 v[20:21], v[78:79], v[80:81]
	v_pk_add_f32 v[0:1], v[0:1], v[18:19]
	s_waitcnt vmcnt(4)
	v_pk_add_f32 v[22:23], v[82:83], v[84:85]
	v_pk_add_f32 v[0:1], v[0:1], v[20:21]
	s_waitcnt vmcnt(3)
	v_pk_add_f32 v[24:25], v[86:87], v[88:89]
	v_pk_add_f32 v[0:1], v[0:1], v[22:23]
	s_waitcnt vmcnt(2)
	v_pk_add_f32 v[26:27], v[90:91], v[92:93]
	v_pk_add_f32 v[0:1], v[0:1], v[24:25]
	s_waitcnt vmcnt(1)
	v_pk_add_f32 v[28:29], v[94:95], v[96:97]
	v_pk_add_f32 v[0:1], v[0:1], v[26:27]
	s_waitcnt vmcnt(0)
	v_pk_add_f32 v[30:31], v[98:99], v[100:101]
	v_pk_add_f32 v[0:1], v[0:1], v[28:29]
	s_nop 0
	v_pk_add_f32 v[0:1], v[0:1], v[30:31]
	s_nop 0
	v_pk_mul_f32 v[0:1], v[0:1], s[22:23] op_sel_hi:[1,0]
	s_nop 0
	v_fma_f32 v1, -v0, v0, v1
	v_add_f32_e32 v1, 0x3727c5ac, v1
	v_mul_f32_e32 v2, 0x4b800000, v1
	v_cmp_gt_f32_e64 s[0:1], s23, v1
	s_nop 1
	v_cndmask_b32_e64 v1, v1, v2, s[0:1]
	v_rsq_f32_e32 v1, v1
	s_nop 0
	v_mul_f32_e32 v2, 0x45800000, v1
	v_cndmask_b32_e64 v1, v1, v2, s[0:1]
	ds_write_b64 v46, v[0:1] offset:34816
; #define LAS __attribute__((address_space(3)))
; __device__ __forceinline__ unsigned cvt_pk_bf16(float lo, float hi) { unsigned r; asm volatile("v_cvt_pk_bf16_f32 %0, %1, %2" : "=v"(r) : "v"(lo), "v"(hi)); return r; }
; __device__ __forceinline__ float bf_lo(unsigned w) { return __uint_as_float(w << 16); }
; __device__ __forceinline__ float bf_hi(unsigned w) { return __uint_as_float(w & 0xffff0000u); }
; __device__ __forceinline__ void sgu_phase(LAS unsigned char* lds, const bf16_t* U, const bf16_t* GV, const bf16_t* SZ, const float* stats, const float* vg, const float* vb,
;                                           const bf16_t* wsb, const float* b_s, bf16_t* Y, int G, int bid) {
;     ...
; #pragma unroll
;         for (int i = 0; i < 4; ++i) {
;             const int id = tid + 512 * i, r = id >> 4, cc = id & 15;
;             const u32x4 w = *(const u32x4*)(GV + (size_t)(row0 + r) * DM + g * 128 + cc * 8);
;             const f32x2 st = rstat[r];
;             const f32x4 g0 = *(const f32x4*)(vg + g * 128 + cc * 8), g1 = *(const f32x4*)(vg + g * 128 + cc * 8 + 4);
;             const f32x4 b0 = *(const f32x4*)(vb + g * 128 + cc * 8), b1 = *(const f32x4*)(vb + g * 128 + cc * 8 + 4);
;             float f[8] = {bf_lo(w.x), bf_hi(w.x), bf_lo(w.y), bf_hi(w.y), bf_lo(w.z), bf_hi(w.z), bf_lo(w.w), bf_hi(w.w)};
; #pragma unroll
;             for (int j = 0; j < 8; ++j) {
;                 const float gg = j < 4 ? g0[j & 3] : g1[j & 3], bb = j < 4 ? b0[j & 3] : b1[j & 3];
;                 const float vn = (f[j] - st.x) * st.y * gg + bb;
;                 *(LAS bf16_t*)(vnT + (cc * 8 + j) * VST + (((r >> 3) ^ cc) << 4) + (r & 7) * 2) = (bf16_t)(cvt_pk_bf16(vn, 0.f) & 0xffffu);
;             }
;         }
.LBB0_237:
	s_or_b64 exec, exec, s[24:25]
	s_lshl_b32 s0, s18, 7
	s_and_b32 s36, s0, 0x780
	v_or_b32_e32 v0, s27, v214
	s_lshl_b32 s18, s36, 1
	v_ashrrev_i32_e32 v1, 31, v0
	v_lshl_add_u64 v[4:5], v[34:35], 0, s[18:19]
	v_lshlrev_b64 v[0:1], 12, v[0:1]
	v_lshl_add_u64 v[0:1], v[4:5], 0, v[0:1]
	s_waitcnt lgkmcnt(0)
	s_barrier
	s_lshl_b32 s18, s36, 2
	v_lshl_add_u64 v[2:3], v[38:39], 0, s[18:19]
	v_lshl_add_u64 v[0:1], v[36:37], 0, s[18:19]
	ds_read_b64 v[26:27], v49 offset:34816
	v_or_b32_e32 v28, s27, v50
	v_ashrrev_i32_e32 v29, 31, v28
	v_lshlrev_b64 v[28:29], 12, v[28:29]
	v_lshl_add_u64 v[28:29], v[4:5], 0, v[28:29]
	s_mov_b64 s[24:25], 0
	v_mov_b32_e32 v69, v41
	v_mov_b32_e32 v70, v64
	s_waitcnt vmcnt(19)
	v_lshlrev_b32_e32 v30, 16, v130
	v_and_b32_e32 v130, 0xffff0000, v130
	v_lshlrev_b32_e32 v44, 16, v133
	v_and_b32_e32 v133, 0xffff0000, v133
	s_waitcnt lgkmcnt(0)
	v_sub_f32_e32 v130, v130, v26
	v_lshlrev_b32_e32 v31, 16, v131
	v_and_b32_e32 v131, 0xffff0000, v131
	v_lshlrev_b32_e32 v32, 16, v132
	v_and_b32_e32 v132, 0xffff0000, v132
	v_sub_f32_e32 v30, v30, v26
	v_sub_f32_e32 v133, v133, v26
	v_mul_f32_e32 v130, v27, v130
	v_sub_f32_e32 v31, v31, v26
	v_sub_f32_e32 v131, v131, v26
	v_sub_f32_e32 v32, v32, v26
	v_sub_f32_e32 v132, v132, v26
	v_sub_f32_e32 v44, v44, v26
	v_mul_f32_e32 v26, v27, v30
	v_mul_f32_e32 v133, v27, v133
	s_waitcnt vmcnt(17)
	v_fma_f32 v130, v139, v130, v135
	v_mul_f32_e32 v30, v27, v31
	v_fma_f32 v134, v138, v26, v134
	s_waitcnt vmcnt(15)
	v_fmac_f32_e32 v149, v145, v133
	v_cvt_pk_bf16_f32 v133, v134, v33
	ds_write_b16 v65, v133
	v_cvt_pk_bf16_f32 v130, v130, v33
	v_mul_f32_e32 v131, v27, v131
	v_fma_f32 v135, v140, v30, v136
	ds_write_b16 v65, v130 offset:272
	v_cvt_pk_bf16_f32 v130, v135, v33
	v_mul_f32_e32 v31, v27, v32
	v_fmac_f32_e32 v137, v141, v131
	ds_write_b16 v65, v130 offset:544
	v_cvt_pk_bf16_f32 v130, v137, v33
	v_mul_f32_e32 v132, v27, v132
	v_fma_f32 v131, v142, v31, v146
	ds_write_b16 v65, v130 offset:816
	v_cvt_pk_bf16_f32 v130, v131, v33
	v_mul_f32_e32 v32, v27, v44
	v_fma_f32 v132, v143, v132, v147
	ds_write_b16 v65, v130 offset:1088
	v_cvt_pk_bf16_f32 v130, v132, v33
	v_fma_f32 v136, v144, v32, v148
	ds_write_b16 v65, v130 offset:1360
	v_cvt_pk_bf16_f32 v130, v136, v33
	ds_write_b16 v65, v130 offset:1632
	v_cvt_pk_bf16_f32 v30, v149, v33
	ds_write_b16 v65, v30 offset:1904
	ds_read_b64 v[28:29], v51 offset:34816
	v_or_b32_e32 v26, s27, v52
	v_ashrrev_i32_e32 v27, 31, v26
	v_lshlrev_b64 v[26:27], 12, v[26:27]
	v_lshl_add_u64 v[26:27], v[4:5], 0, v[26:27]
	s_waitcnt vmcnt(14)
	v_lshlrev_b32_e32 v30, 16, v170
	v_and_b32_e32 v170, 0xffff0000, v170
	v_lshlrev_b32_e32 v44, 16, v173
	v_and_b32_e32 v173, 0xffff0000, v173
	s_waitcnt lgkmcnt(0)
	v_sub_f32_e32 v170, v170, v28
	v_lshlrev_b32_e32 v31, 16, v171
	v_and_b32_e32 v171, 0xffff0000, v171
	v_lshlrev_b32_e32 v32, 16, v172
	v_and_b32_e32 v172, 0xffff0000, v172
	v_sub_f32_e32 v30, v30, v28
	v_sub_f32_e32 v173, v173, v28
	v_mul_f32_e32 v170, v29, v170
	v_sub_f32_e32 v31, v31, v28
	v_sub_f32_e32 v171, v171, v28
	v_sub_f32_e32 v32, v32, v28
	v_sub_f32_e32 v172, v172, v28
	v_sub_f32_e32 v44, v44, v28
	v_mul_f32_e32 v28, v29, v30
	v_mul_f32_e32 v173, v29, v173
	s_waitcnt vmcnt(12)
	v_fma_f32 v170, v179, v170, v175
	v_mul_f32_e32 v30, v29, v31
	v_fma_f32 v174, v178, v28, v174
	s_waitcnt vmcnt(10)
	v_fmac_f32_e32 v189, v185, v173
	v_cvt_pk_bf16_f32 v173, v174, v33
	ds_write_b16 v66, v173
	v_cvt_pk_bf16_f32 v170, v170, v33
	v_mul_f32_e32 v171, v29, v171
	v_fma_f32 v175, v180, v30, v176
	ds_write_b16 v66, v170 offset:272
	v_cvt_pk_bf16_f32 v170, v175, v33
	v_mul_f32_e32 v31, v29, v32
	v_fmac_f32_e32 v177, v181, v171
	ds_write_b16 v66, v170 offset:544
	v_cvt_pk_bf16_f32 v170, v177, v33
	v_mul_f32_e32 v172, v29, v172
	v_fma_f32 v171, v182, v31, v186
	ds_write_b16 v66, v170 offset:816
	v_cvt_pk_bf16_f32 v170, v171, v33
	v_mul_f32_e32 v32, v29, v44
	v_fma_f32 v172, v183, v172, v187
	ds_write_b16 v66, v170 offset:1088
	v_cvt_pk_bf16_f32 v170, v172, v33
	v_fma_f32 v176, v184, v32, v188
	ds_write_b16 v66, v170 offset:1360
	v_cvt_pk_bf16_f32 v170, v176, v33
	ds_write_b16 v66, v170 offset:1632
	v_cvt_pk_bf16_f32 v28, v189, v33
	v_add_u32_e32 v26, s27, v54
	v_ashrrev_i32_e32 v27, 31, v26
	v_lshlrev_b64 v[26:27], 12, v[26:27]
	ds_write_b16 v66, v28 offset:1904
	v_lshl_add_u64 v[4:5], v[4:5], 0, v[26:27]
	ds_read_b64 v[26:27], v53 offset:34816
	v_add_lshl_u32 v32, v47, s36, 8
	v_lshl_add_u64 v[44:45], v[42:43], 0, v[32:33]
	s_waitcnt vmcnt(9)
; #define LAS __attribute__((address_space(3)))
; __device__ __forceinline__ unsigned cvt_pk_bf16(float lo, float hi) { unsigned r; asm volatile("v_cvt_pk_bf16_f32 %0, %1, %2" : "=v"(r) : "v"(lo), "v"(hi)); return r; }
; __device__ __forceinline__ float bf_lo(unsigned w) { return __uint_as_float(w << 16); }
; __device__ __forceinline__ float bf_hi(unsigned w) { return __uint_as_float(w & 0xffff0000u); }
; __device__ __forceinline__ void sgu_phase(LAS unsigned char* lds, const bf16_t* U, const bf16_t* GV, const bf16_t* SZ, const float* stats, const float* vg, const float* vb,
;                                           const bf16_t* wsb, const float* b_s, bf16_t* Y, int G, int bid) {
;     ...
; #pragma unroll
;         for (int i = 0; i < 4; ++i) {
;             const int id = tid + 512 * i, r = id >> 4, cc = id & 15;
;             const u32x4 w = *(const u32x4*)(GV + (size_t)(row0 + r) * DM + g * 128 + cc * 8);
;             const f32x2 st = rstat[r];
;             const f32x4 g0 = *(const f32x4*)(vg + g * 128 + cc * 8), g1 = *(const f32x4*)(vg + g * 128 + cc * 8 + 4);
;             const f32x4 b0 = *(const f32x4*)(vb + g * 128 + cc * 8), b1 = *(const f32x4*)(vb + g * 128 + cc * 8 + 4);
;             float f[8] = {bf_lo(w.x), bf_hi(w.x), bf_lo(w.y), bf_hi(w.y), bf_lo(w.z), bf_hi(w.z), bf_lo(w.w), bf_hi(w.w)};
; #pragma unroll
;             for (int j = 0; j < 8; ++j) {
;                 const float gg = j < 4 ? g0[j & 3] : g1[j & 3], bb = j < 4 ? b0[j & 3] : b1[j & 3];
;                 const float vn = (f[j] - st.x) * st.y * gg + bb;
;                 *(LAS bf16_t*)(vnT + (cc * 8 + j) * VST + (((r >> 3) ^ cc) << 4) + (r & 7) * 2) = (bf16_t)(cvt_pk_bf16(vn, 0.f) & 0xffffu);
;             }
;         }
;         __syncthreads();
;         f32x4 acc[8];
; #pragma unroll
;         for (int ct = 0; ct < 8; ++ct) acc[ct] = (f32x4){0.f, 0.f, 0.f, 0.f};
	v_lshlrev_b32_e32 v28, 16, v190
	v_and_b32_e32 v190, 0xffff0000, v190
	v_lshlrev_b32_e32 v31, 16, v193
	v_and_b32_e32 v193, 0xffff0000, v193
	s_waitcnt lgkmcnt(0)
	v_sub_f32_e32 v190, v190, v26
	v_lshlrev_b32_e32 v29, 16, v191
	v_and_b32_e32 v191, 0xffff0000, v191
	v_lshlrev_b32_e32 v30, 16, v192
	v_and_b32_e32 v192, 0xffff0000, v192
	v_sub_f32_e32 v28, v28, v26
	v_sub_f32_e32 v193, v193, v26
	v_mul_f32_e32 v190, v27, v190
	v_sub_f32_e32 v29, v29, v26
	v_sub_f32_e32 v191, v191, v26
	v_sub_f32_e32 v30, v30, v26
	v_sub_f32_e32 v192, v192, v26
	v_sub_f32_e32 v31, v31, v26
	v_mul_f32_e32 v26, v27, v28
	v_mul_f32_e32 v193, v27, v193
	s_waitcnt vmcnt(7)
	v_fma_f32 v190, v199, v190, v195
	v_mul_f32_e32 v28, v27, v29
	v_fma_f32 v194, v198, v26, v194
	s_waitcnt vmcnt(5)
	v_fmac_f32_e32 v209, v205, v193
	v_cvt_pk_bf16_f32 v193, v194, v33
	ds_write_b16 v67, v193
	v_cvt_pk_bf16_f32 v190, v190, v33
	v_mul_f32_e32 v191, v27, v191
	v_fma_f32 v195, v200, v28, v196
	ds_write_b16 v67, v190 offset:272
	v_cvt_pk_bf16_f32 v190, v195, v33
	v_mul_f32_e32 v29, v27, v30
	v_fmac_f32_e32 v197, v201, v191
	ds_write_b16 v67, v190 offset:544
	v_cvt_pk_bf16_f32 v190, v197, v33
	v_mul_f32_e32 v192, v27, v192
	v_fma_f32 v191, v202, v29, v206
	ds_write_b16 v67, v190 offset:816
	v_cvt_pk_bf16_f32 v190, v191, v33
	v_mul_f32_e32 v30, v27, v31
	v_fma_f32 v192, v203, v192, v207
	ds_write_b16 v67, v190 offset:1088
	v_cvt_pk_bf16_f32 v190, v192, v33
	v_fma_f32 v196, v204, v30, v208
	ds_write_b16 v67, v190 offset:1360
	v_cvt_pk_bf16_f32 v190, v196, v33
	ds_write_b16 v67, v190 offset:1632
	v_cvt_pk_bf16_f32 v31, v209, v33
	ds_write_b16 v67, v31 offset:1904
	ds_read_b64 v[92:93], v55 offset:34816
	v_mov_b32_e32 v0, 0
	v_mov_b32_e32 v1, v0
	v_mov_b32_e32 v2, v0
	v_mov_b32_e32 v3, v0
	v_mov_b32_e32 v4, v0
	v_mov_b32_e32 v5, v0
	v_mov_b32_e32 v6, v0
	v_mov_b32_e32 v7, v0
	v_mov_b32_e32 v8, v0
	v_mov_b32_e32 v9, v0
	v_mov_b32_e32 v10, v0
	v_mov_b32_e32 v11, v0
	v_mov_b32_e32 v12, v0
	v_mov_b32_e32 v13, v0
	v_mov_b32_e32 v14, v0
	v_mov_b32_e32 v15, v0
	v_mov_b32_e32 v16, v0
	v_mov_b32_e32 v17, v0
	v_mov_b32_e32 v18, v0
	v_mov_b32_e32 v19, v0
	v_mov_b32_e32 v20, v0
	v_mov_b32_e32 v21, v0
	v_mov_b32_e32 v22, v0
	v_mov_b32_e32 v23, v0
	v_mov_b32_e32 v24, v0
	v_mov_b32_e32 v25, v0
	v_mov_b32_e32 v26, v0
	v_mov_b32_e32 v27, v0
	v_mov_b32_e32 v28, v0
	v_mov_b32_e32 v29, v0
	v_mov_b32_e32 v30, v0
	s_waitcnt vmcnt(4)
	v_lshlrev_b32_e32 v31, 16, v216
	s_waitcnt lgkmcnt(0)
	v_sub_f32_e32 v31, v31, v92
	v_and_b32_e32 v32, 0xffff0000, v216
	v_mul_f32_e32 v31, v93, v31
	v_lshlrev_b32_e32 v71, 16, v217
	v_sub_f32_e32 v32, v32, v92
	s_waitcnt vmcnt(2)
	v_fma_f32 v31, v224, v31, v220
	v_and_b32_e32 v216, 0xffff0000, v217
	v_sub_f32_e32 v71, v71, v92
	v_mul_f32_e32 v32, v93, v32
	v_cvt_pk_bf16_f32 v31, v31, v33
	v_lshlrev_b32_e32 v217, 16, v218
	v_sub_f32_e32 v216, v216, v92
	v_mul_f32_e32 v71, v93, v71
	v_fma_f32 v32, v225, v32, v221
	ds_write_b16 v68, v31
	v_cvt_pk_bf16_f32 v31, v32, v33
	v_and_b32_e32 v218, 0xffff0000, v218
	v_sub_f32_e32 v217, v217, v92
	v_mul_f32_e32 v216, v93, v216
	v_fma_f32 v71, v226, v71, v222
	ds_write_b16 v68, v31 offset:272
	v_cvt_pk_bf16_f32 v31, v71, v33
	v_lshlrev_b32_e32 v94, 16, v219
	v_sub_f32_e32 v218, v218, v92
	v_mul_f32_e32 v217, v93, v217
	v_fmac_f32_e32 v223, v227, v216
	ds_write_b16 v68, v31 offset:544
	v_cvt_pk_bf16_f32 v31, v223, v33
	v_and_b32_e32 v219, 0xffff0000, v219
	v_sub_f32_e32 v94, v94, v92
	v_mul_f32_e32 v218, v93, v218
	s_waitcnt vmcnt(0)
	v_fma_f32 v216, v228, v217, v232
	ds_write_b16 v68, v31 offset:816
	v_cvt_pk_bf16_f32 v31, v216, v33
	v_sub_f32_e32 v219, v219, v92
	v_mul_f32_e32 v92, v93, v94
	v_fma_f32 v217, v229, v218, v233
	ds_write_b16 v68, v31 offset:1088
	v_cvt_pk_bf16_f32 v31, v217, v33
	v_mul_f32_e32 v219, v93, v219
	v_fma_f32 v218, v230, v92, v234
	ds_write_b16 v68, v31 offset:1360
	v_cvt_pk_bf16_f32 v31, v218, v33
	v_fmac_f32_e32 v235, v231, v219
	ds_write_b16 v68, v31 offset:1632
	v_cvt_pk_bf16_f32 v31, v235, v33
	ds_write_b16 v68, v31 offset:1904
	v_mov_b32_e32 v31, v0
	s_waitcnt lgkmcnt(0)
	s_barrier
